# squared-ReLU GEMM epilogues without the redundant canonicalizing v_max (107 VALU per tile fewer), conservative s_nop pads
# baseline (speedup 1.0000x reference)
.LBB0_840:
	s_nop 7
	s_nop 7
	v_lshl_add_u32 v152, s30, 8, v146
	v_ashrrev_i32_e32 v153, 31, v152
	v_max_f32_e32 v120, 0, v120
	v_lshl_or_b32 v144, s33, 8, v148
	v_lshlrev_b64 v[154:155], 13, v[152:153]
	v_mul_f32_e32 v153, v120, v120
	v_max_f32_e32 v121, 0, v121
	v_max_f32_e32 v122, 0, v122
	v_ashrrev_i32_e32 v145, 31, v144
	v_max_f32_e32 v120, 0, v125
	v_mul_f32_e32 v125, v121, v121
	v_max_f32_e32 v121, v126, v126
	v_mul_f32_e32 v126, v122, v122
	v_lshl_add_u64 v[154:155], s[56:57], 0, v[154:155]
	v_lshlrev_b64 v[156:157], 1, v[144:145]
	v_max_f32_e32 v124, 0, v124
	v_mul_f32_e32 v120, v120, v120
	v_max_f32_e32 v121, 0, v121
	v_max_f32_e32 v122, 0, v127
	v_max_f32_e32 v123, 0, v123
	v_lshl_add_u64 v[144:145], v[154:155], 0, v[156:157]
	v_mul_f32_e32 v124, v124, v124
	v_mul_f32_e32 v121, v121, v121
	v_mul_f32_e32 v122, v122, v122
	v_mul_f32_e32 v123, v123, v123
	v_cvt_pk_bf16_f32 v120, v124, v120
	v_max_f32_e32 v112, 0, v112
	v_cvt_pk_bf16_f32 v121, v121, v122
	v_cvt_pk_bf16_f32 v122, v153, v125
	v_cvt_pk_bf16_f32 v123, v126, v123
	global_store_dwordx4 v[144:145], v[120:123], off
	s_nop 1
	v_max_f32_e32 v113, 0, v113
	v_max_f32_e32 v114, 0, v114
	v_mul_f32_e32 v120, v112, v112
	v_max_f32_e32 v112, 0, v117
	v_mul_f32_e32 v117, v113, v113
	v_max_f32_e32 v113, v118, v118
	v_mul_f32_e32 v118, v114, v114
	v_max_f32_e32 v116, 0, v116
	v_mul_f32_e32 v112, v112, v112
	v_max_f32_e32 v113, 0, v113
	v_max_f32_e32 v114, 0, v119
	v_max_f32_e32 v115, 0, v115
	v_mul_f32_e32 v116, v116, v116
	v_mul_f32_e32 v113, v113, v113
	v_mul_f32_e32 v114, v114, v114
	v_mul_f32_e32 v115, v115, v115
	v_cvt_pk_bf16_f32 v112, v116, v112
	v_cvt_pk_bf16_f32 v113, v113, v114
	v_cvt_pk_bf16_f32 v114, v120, v117
	v_cvt_pk_bf16_f32 v115, v118, v115
	global_store_dwordx4 v[144:145], v[112:115], off offset:256
	s_nop 1
	v_max_f32_e32 v104, 0, v104
	v_or_b32_e32 v112, 16, v152
	v_ashrrev_i32_e32 v113, 31, v112
	v_mul_f32_e32 v114, v104, v104
	v_max_f32_e32 v105, 0, v105
	v_max_f32_e32 v106, 0, v106
	v_lshlrev_b64 v[112:113], 13, v[112:113]
	v_max_f32_e32 v104, 0, v109
	v_mul_f32_e32 v109, v105, v105
	v_max_f32_e32 v105, v110, v110
	v_mul_f32_e32 v110, v106, v106
	v_lshl_add_u64 v[112:113], s[56:57], 0, v[112:113]
	v_max_f32_e32 v108, 0, v108
	v_mul_f32_e32 v104, v104, v104
	v_max_f32_e32 v105, 0, v105
	v_max_f32_e32 v106, 0, v111
	v_max_f32_e32 v107, 0, v107
	v_lshl_add_u64 v[112:113], v[112:113], 0, v[156:157]
	v_mul_f32_e32 v108, v108, v108
	v_mul_f32_e32 v105, v105, v105
	v_mul_f32_e32 v106, v106, v106
	v_mul_f32_e32 v107, v107, v107
	v_cvt_pk_bf16_f32 v104, v108, v104
	v_max_f32_e32 v96, 0, v96
	v_cvt_pk_bf16_f32 v105, v105, v106
	v_cvt_pk_bf16_f32 v106, v114, v109
	v_cvt_pk_bf16_f32 v107, v110, v107
	global_store_dwordx4 v[112:113], v[104:107], off
	s_nop 1
	v_max_f32_e32 v97, 0, v97
	v_max_f32_e32 v98, 0, v98
	v_mul_f32_e32 v104, v96, v96
	v_max_f32_e32 v96, 0, v101
	v_mul_f32_e32 v101, v97, v97
	v_max_f32_e32 v97, v102, v102
	v_mul_f32_e32 v102, v98, v98
	v_max_f32_e32 v100, 0, v100
	v_mul_f32_e32 v96, v96, v96
	v_max_f32_e32 v97, 0, v97
	v_max_f32_e32 v98, 0, v103
	v_max_f32_e32 v99, 0, v99
	v_mul_f32_e32 v100, v100, v100
	v_mul_f32_e32 v97, v97, v97
	v_mul_f32_e32 v98, v98, v98
	v_mul_f32_e32 v99, v99, v99
	v_cvt_pk_bf16_f32 v96, v100, v96
	v_cvt_pk_bf16_f32 v97, v97, v98
	v_cvt_pk_bf16_f32 v98, v104, v101
	v_cvt_pk_bf16_f32 v99, v102, v99
	global_store_dwordx4 v[112:113], v[96:99], off offset:256
	s_nop 1
	v_max_f32_e32 v88, 0, v88
	v_or_b32_e32 v96, 32, v152
	v_ashrrev_i32_e32 v97, 31, v96
	v_mul_f32_e32 v98, v88, v88
	v_max_f32_e32 v89, 0, v89
	v_max_f32_e32 v90, 0, v90
	v_lshlrev_b64 v[96:97], 13, v[96:97]
	v_max_f32_e32 v88, 0, v93
	v_mul_f32_e32 v93, v89, v89
	v_max_f32_e32 v89, v94, v94
	v_mul_f32_e32 v94, v90, v90
	v_lshl_add_u64 v[96:97], s[56:57], 0, v[96:97]
	v_max_f32_e32 v92, 0, v92
	v_mul_f32_e32 v88, v88, v88
	v_max_f32_e32 v89, 0, v89
	v_max_f32_e32 v90, 0, v95
	v_max_f32_e32 v91, 0, v91
	v_lshl_add_u64 v[96:97], v[96:97], 0, v[156:157]
	v_mul_f32_e32 v92, v92, v92
	v_mul_f32_e32 v89, v89, v89
	v_mul_f32_e32 v90, v90, v90
	v_mul_f32_e32 v91, v91, v91
	v_cvt_pk_bf16_f32 v88, v92, v88
	v_max_f32_e32 v80, 0, v80
	v_cvt_pk_bf16_f32 v89, v89, v90
	v_cvt_pk_bf16_f32 v90, v98, v93
	v_cvt_pk_bf16_f32 v91, v94, v91
	global_store_dwordx4 v[96:97], v[88:91], off
	s_nop 1
	v_max_f32_e32 v81, 0, v81
	v_max_f32_e32 v82, 0, v82
	v_mul_f32_e32 v88, v80, v80
	v_max_f32_e32 v80, 0, v85
	v_mul_f32_e32 v85, v81, v81
	v_max_f32_e32 v81, v86, v86
	v_mul_f32_e32 v86, v82, v82
	v_max_f32_e32 v84, 0, v84
	v_mul_f32_e32 v80, v80, v80
	v_max_f32_e32 v81, 0, v81
	v_max_f32_e32 v82, 0, v87
	v_max_f32_e32 v83, 0, v83
	v_mul_f32_e32 v84, v84, v84
	v_mul_f32_e32 v81, v81, v81
	v_mul_f32_e32 v82, v82, v82
	v_mul_f32_e32 v83, v83, v83
	v_cvt_pk_bf16_f32 v80, v84, v80
	v_cvt_pk_bf16_f32 v81, v81, v82
	v_cvt_pk_bf16_f32 v82, v88, v85
	v_cvt_pk_bf16_f32 v83, v86, v83
	global_store_dwordx4 v[96:97], v[80:83], off offset:256
	s_nop 1
	v_max_f32_e32 v72, 0, v72
	v_or_b32_e32 v80, 48, v152
	v_ashrrev_i32_e32 v81, 31, v80
	v_mul_f32_e32 v82, v72, v72
	v_max_f32_e32 v73, 0, v73
	v_max_f32_e32 v74, 0, v74
	v_lshlrev_b64 v[80:81], 13, v[80:81]
	v_max_f32_e32 v72, 0, v77
	v_mul_f32_e32 v77, v73, v73
	v_max_f32_e32 v73, v78, v78
	v_mul_f32_e32 v78, v74, v74
	v_lshl_add_u64 v[80:81], s[56:57], 0, v[80:81]
	v_max_f32_e32 v76, 0, v76
	v_mul_f32_e32 v72, v72, v72
	v_max_f32_e32 v73, 0, v73
	v_max_f32_e32 v74, 0, v79
	v_max_f32_e32 v75, 0, v75
	v_lshl_add_u64 v[80:81], v[80:81], 0, v[156:157]
	v_mul_f32_e32 v76, v76, v76
	v_mul_f32_e32 v73, v73, v73
	v_mul_f32_e32 v74, v74, v74
	v_mul_f32_e32 v75, v75, v75
	v_cvt_pk_bf16_f32 v72, v76, v72
	v_max_f32_e32 v64, 0, v64
	v_max_f32_e32 v65, 0, v65
	v_max_f32_e32 v66, 0, v66
	v_cvt_pk_bf16_f32 v73, v73, v74
	v_cvt_pk_bf16_f32 v74, v82, v77
	v_cvt_pk_bf16_f32 v75, v78, v75
	global_store_dwordx4 v[80:81], v[72:75], off
	s_nop 1
	v_mul_f32_e32 v72, v64, v64
	v_max_f32_e32 v64, v69, v69
	v_mul_f32_e32 v69, v65, v65
	v_max_f32_e32 v65, v70, v70
	v_mul_f32_e32 v70, v66, v66
	v_max_f32_e32 v64, 0, v64
	v_max_f32_e32 v65, 0, v65
	v_max_f32_e32 v66, 0, v71
	v_max_f32_e32 v68, 0, v68
	v_mul_f32_e32 v64, v64, v64
	v_mul_f32_e32 v65, v65, v65
	v_max_f32_e32 v67, 0, v67
	v_mul_f32_e32 v66, v66, v66
	v_mul_f32_e32 v68, v68, v68
	v_mul_f32_e32 v67, v67, v67
	v_cvt_pk_bf16_f32 v64, v68, v64
	v_cvt_pk_bf16_f32 v65, v65, v66
	v_cvt_pk_bf16_f32 v66, v72, v69
	v_max_f32_e32 v56, 0, v56
	v_cvt_pk_bf16_f32 v67, v70, v67
	global_store_dwordx4 v[80:81], v[64:67], off offset:256
	s_nop 1
	v_max_f32_e32 v57, 0, v57
	v_mul_f32_e32 v66, v56, v56
	v_max_f32_e32 v58, 0, v58
	v_max_f32_e32 v60, 0, v60
	v_max_f32_e32 v56, 0, v61
	v_mul_f32_e32 v61, v57, v57
	v_max_f32_e32 v57, v62, v62
	v_mul_f32_e32 v62, v58, v58
	v_mul_f32_e32 v60, v60, v60
	v_mul_f32_e32 v56, v56, v56
	v_max_f32_e32 v57, 0, v57
	v_max_f32_e32 v58, 0, v63
	v_mul_f32_e32 v57, v57, v57
	v_max_f32_e32 v59, 0, v59
	v_mul_f32_e32 v58, v58, v58
	v_cvt_pk_bf16_f32 v56, v60, v56
	v_add_co_u32_e32 v60, vcc, s71, v144
	v_mul_f32_e32 v59, v59, v59
	v_cvt_pk_bf16_f32 v57, v57, v58
	v_cvt_pk_bf16_f32 v58, v66, v61
	v_addc_co_u32_e32 v61, vcc, 0, v145, vcc
	v_max_f32_e32 v48, 0, v48
	v_max_f32_e32 v49, 0, v49
	v_max_f32_e32 v50, 0, v50
	v_cvt_pk_bf16_f32 v59, v62, v59
	global_store_dwordx4 v[60:61], v[56:59], off
	s_nop 1
	v_mul_f32_e32 v56, v48, v48
	v_max_f32_e32 v48, v53, v53
	v_mul_f32_e32 v53, v49, v49
	v_max_f32_e32 v49, v54, v54
	v_mul_f32_e32 v54, v50, v50
	v_max_f32_e32 v48, 0, v48
	v_max_f32_e32 v49, 0, v49
	v_max_f32_e32 v50, 0, v55
	v_max_f32_e32 v52, 0, v52
	v_mul_f32_e32 v48, v48, v48
	v_mul_f32_e32 v49, v49, v49
	v_max_f32_e32 v51, 0, v51
	v_mul_f32_e32 v50, v50, v50
	v_lshl_add_u64 v[64:65], v[144:145], 0, s[14:15]
	v_mul_f32_e32 v52, v52, v52
	v_mul_f32_e32 v51, v51, v51
	v_cvt_pk_bf16_f32 v48, v52, v48
	v_cvt_pk_bf16_f32 v49, v49, v50
	v_cvt_pk_bf16_f32 v50, v56, v53
	v_max_f32_e32 v40, 0, v40
	v_cvt_pk_bf16_f32 v51, v54, v51
	global_store_dwordx4 v[64:65], v[48:51], off offset:256
	s_nop 1
	v_max_f32_e32 v41, 0, v41
	v_mul_f32_e32 v50, v40, v40
	v_max_f32_e32 v42, 0, v42
	v_max_f32_e32 v44, 0, v44
	v_max_f32_e32 v40, 0, v45
	v_mul_f32_e32 v45, v41, v41
	v_max_f32_e32 v41, v46, v46
	v_mul_f32_e32 v46, v42, v42
	v_mul_f32_e32 v44, v44, v44
	v_mul_f32_e32 v40, v40, v40
	v_max_f32_e32 v41, 0, v41
	v_max_f32_e32 v42, 0, v47
	v_mul_f32_e32 v41, v41, v41
	v_max_f32_e32 v43, 0, v43
	v_mul_f32_e32 v42, v42, v42
	v_cvt_pk_bf16_f32 v40, v44, v40
	v_add_co_u32_e32 v44, vcc, s72, v144
	v_mul_f32_e32 v43, v43, v43
	v_cvt_pk_bf16_f32 v41, v41, v42
	v_cvt_pk_bf16_f32 v42, v50, v45
	v_addc_co_u32_e32 v45, vcc, 0, v145, vcc
	v_max_f32_e32 v32, 0, v32
	v_max_f32_e32 v33, 0, v33
	v_max_f32_e32 v34, 0, v34
	v_cvt_pk_bf16_f32 v43, v46, v43
	global_store_dwordx4 v[44:45], v[40:43], off
	s_nop 1
	v_mul_f32_e32 v40, v32, v32
	v_max_f32_e32 v32, v37, v37
	v_mul_f32_e32 v37, v33, v33
	v_max_f32_e32 v33, v38, v38
	v_mul_f32_e32 v38, v34, v34
	v_max_f32_e32 v32, 0, v32
	v_max_f32_e32 v33, 0, v33
	v_max_f32_e32 v34, 0, v39
	v_max_f32_e32 v36, 0, v36
	v_mul_f32_e32 v32, v32, v32
	v_mul_f32_e32 v33, v33, v33
	v_max_f32_e32 v35, 0, v35
	v_mul_f32_e32 v34, v34, v34
	v_lshl_add_u64 v[48:49], v[144:145], 0, s[16:17]
	v_mul_f32_e32 v36, v36, v36
	v_mul_f32_e32 v35, v35, v35
	v_cvt_pk_bf16_f32 v32, v36, v32
	v_cvt_pk_bf16_f32 v33, v33, v34
	v_cvt_pk_bf16_f32 v34, v40, v37
	v_max_f32_e32 v24, 0, v24
	v_cvt_pk_bf16_f32 v35, v38, v35
	global_store_dwordx4 v[48:49], v[32:35], off offset:256
	s_nop 1
	v_max_f32_e32 v25, 0, v25
	v_mul_f32_e32 v34, v24, v24
	v_max_f32_e32 v26, 0, v26
	v_max_f32_e32 v28, 0, v28
	v_max_f32_e32 v24, 0, v29
	v_mul_f32_e32 v29, v25, v25
	v_max_f32_e32 v25, v30, v30
	v_mul_f32_e32 v30, v26, v26
	v_mul_f32_e32 v28, v28, v28
	v_mul_f32_e32 v24, v24, v24
	v_max_f32_e32 v25, 0, v25
	v_max_f32_e32 v26, 0, v31
	v_mul_f32_e32 v25, v25, v25
	v_max_f32_e32 v27, 0, v27
	v_mul_f32_e32 v26, v26, v26
	v_cvt_pk_bf16_f32 v24, v28, v24
	v_add_co_u32_e32 v28, vcc, s73, v144
	v_mul_f32_e32 v27, v27, v27
	v_cvt_pk_bf16_f32 v25, v25, v26
	v_cvt_pk_bf16_f32 v26, v34, v29
	v_addc_co_u32_e32 v29, vcc, 0, v145, vcc
	v_max_f32_e32 v16, 0, v16
	v_max_f32_e32 v17, 0, v17
	v_max_f32_e32 v18, 0, v18
	v_cvt_pk_bf16_f32 v27, v30, v27
	global_store_dwordx4 v[28:29], v[24:27], off
	s_nop 1
	v_mul_f32_e32 v24, v16, v16
	v_max_f32_e32 v16, v21, v21
	v_mul_f32_e32 v21, v17, v17
	v_max_f32_e32 v17, v22, v22
	v_mul_f32_e32 v22, v18, v18
	v_max_f32_e32 v16, 0, v16
	v_max_f32_e32 v17, 0, v17
	v_max_f32_e32 v18, 0, v23
	v_max_f32_e32 v20, 0, v20
	v_mul_f32_e32 v16, v16, v16
	v_mul_f32_e32 v17, v17, v17
	v_max_f32_e32 v19, 0, v19
	v_mul_f32_e32 v18, v18, v18
	v_lshl_add_u64 v[32:33], v[144:145], 0, s[18:19]
	v_mul_f32_e32 v20, v20, v20
	v_mul_f32_e32 v19, v19, v19
	v_cvt_pk_bf16_f32 v16, v20, v16
	v_cvt_pk_bf16_f32 v17, v17, v18
	v_cvt_pk_bf16_f32 v18, v24, v21
	v_max_f32_e32 v8, 0, v8
	v_cvt_pk_bf16_f32 v19, v22, v19
	global_store_dwordx4 v[32:33], v[16:19], off offset:256
	s_nop 1
	v_max_f32_e32 v9, 0, v9
	v_mul_f32_e32 v18, v8, v8
	v_max_f32_e32 v10, 0, v10
	v_max_f32_e32 v12, 0, v12
	v_max_f32_e32 v8, 0, v13
	v_mul_f32_e32 v13, v9, v9
	v_max_f32_e32 v9, v14, v14
	v_mul_f32_e32 v14, v10, v10
	v_mul_f32_e32 v12, v12, v12
	v_mul_f32_e32 v8, v8, v8
	v_max_f32_e32 v9, 0, v9
	v_max_f32_e32 v10, 0, v15
	v_mul_f32_e32 v9, v9, v9
	v_max_f32_e32 v11, 0, v11
	v_mul_f32_e32 v10, v10, v10
	v_cvt_pk_bf16_f32 v8, v12, v8
	v_add_co_u32_e32 v12, vcc, s74, v144
	v_mul_f32_e32 v11, v11, v11
	v_cvt_pk_bf16_f32 v9, v9, v10
	v_cvt_pk_bf16_f32 v10, v18, v13
	v_addc_co_u32_e32 v13, vcc, 0, v145, vcc
	v_max_f32_e32 v0, 0, v0
	v_max_f32_e32 v1, 0, v1
	v_max_f32_e32 v2, 0, v2
	v_cvt_pk_bf16_f32 v11, v14, v11
	global_store_dwordx4 v[12:13], v[8:11], off
	s_nop 1
	v_mul_f32_e32 v8, v0, v0
	v_max_f32_e32 v0, v5, v5
	v_mul_f32_e32 v5, v1, v1
	v_max_f32_e32 v1, v6, v6
	v_mul_f32_e32 v6, v2, v2
	v_max_f32_e32 v0, 0, v0
	v_max_f32_e32 v1, 0, v1
	v_max_f32_e32 v2, 0, v7
	v_max_f32_e32 v3, 0, v3
	v_lshl_add_u64 v[16:17], v[144:145], 0, s[20:21]
	v_max_f32_e32 v4, 0, v4
	v_mul_f32_e32 v0, v0, v0
	v_mul_f32_e32 v1, v1, v1
	v_mul_f32_e32 v2, v2, v2
	v_mul_f32_e32 v3, v3, v3
	s_andn2_b64 vcc, exec, s[4:5]
	s_mov_b64 s[4:5], -1
	v_mul_f32_e32 v4, v4, v4
	v_cvt_pk_bf16_f32 v0, v4, v0
	v_cvt_pk_bf16_f32 v1, v1, v2
	v_cvt_pk_bf16_f32 v2, v8, v5
	v_cvt_pk_bf16_f32 v3, v6, v3
	global_store_dwordx4 v[16:17], v[0:3], off offset:256
	s_nop 1
	s_cbranch_vccnz .LBB0_829
	s_andn2_b64 vcc, exec, s[8:9]
	s_cbranch_vccnz .LBB0_828
	s_barrier
	s_branch .LBB0_828

.LBB0_1574:
	s_nop 7
	s_nop 7
	v_lshl_add_u32 v152, s28, 8, v146
	v_ashrrev_i32_e32 v153, 31, v152
	v_max_f32_e32 v120, 0, v120
	v_lshl_or_b32 v144, s33, 8, v148
	v_lshlrev_b64 v[154:155], 13, v[152:153]
	v_mul_f32_e32 v153, v120, v120
	v_max_f32_e32 v121, 0, v121
	v_max_f32_e32 v122, 0, v122
	v_ashrrev_i32_e32 v145, 31, v144
	v_max_f32_e32 v120, 0, v125
	v_mul_f32_e32 v125, v121, v121
	v_max_f32_e32 v121, v126, v126
	v_mul_f32_e32 v126, v122, v122
	v_lshl_add_u64 v[154:155], s[56:57], 0, v[154:155]
	v_lshlrev_b64 v[156:157], 1, v[144:145]
	v_max_f32_e32 v124, 0, v124
	v_mul_f32_e32 v120, v120, v120
	v_max_f32_e32 v121, 0, v121
	v_max_f32_e32 v122, 0, v127
	v_max_f32_e32 v123, 0, v123
	v_lshl_add_u64 v[144:145], v[154:155], 0, v[156:157]
	v_mul_f32_e32 v124, v124, v124
	v_mul_f32_e32 v121, v121, v121
	v_mul_f32_e32 v122, v122, v122
	v_mul_f32_e32 v123, v123, v123
	v_cvt_pk_bf16_f32 v120, v124, v120
	v_max_f32_e32 v112, 0, v112
	v_cvt_pk_bf16_f32 v121, v121, v122
	v_cvt_pk_bf16_f32 v122, v153, v125
	v_cvt_pk_bf16_f32 v123, v126, v123
	global_store_dwordx4 v[144:145], v[120:123], off
	s_nop 1
	v_max_f32_e32 v113, 0, v113
	v_max_f32_e32 v114, 0, v114
	v_mul_f32_e32 v120, v112, v112
	v_max_f32_e32 v112, 0, v117
	v_mul_f32_e32 v117, v113, v113
	v_max_f32_e32 v113, v118, v118
	v_mul_f32_e32 v118, v114, v114
	v_max_f32_e32 v116, 0, v116
	v_mul_f32_e32 v112, v112, v112
	v_max_f32_e32 v113, 0, v113
	v_max_f32_e32 v114, 0, v119
	v_max_f32_e32 v115, 0, v115
	v_mul_f32_e32 v116, v116, v116
	v_mul_f32_e32 v113, v113, v113
	v_mul_f32_e32 v114, v114, v114
	v_mul_f32_e32 v115, v115, v115
	v_cvt_pk_bf16_f32 v112, v116, v112
	v_cvt_pk_bf16_f32 v113, v113, v114
	v_cvt_pk_bf16_f32 v114, v120, v117
	v_cvt_pk_bf16_f32 v115, v118, v115
	global_store_dwordx4 v[144:145], v[112:115], off offset:256
	s_nop 1
	v_max_f32_e32 v104, 0, v104
	v_or_b32_e32 v112, 16, v152
	v_ashrrev_i32_e32 v113, 31, v112
	v_mul_f32_e32 v114, v104, v104
	v_max_f32_e32 v105, 0, v105
	v_max_f32_e32 v106, 0, v106
	v_lshlrev_b64 v[112:113], 13, v[112:113]
	v_max_f32_e32 v104, 0, v109
	v_mul_f32_e32 v109, v105, v105
	v_max_f32_e32 v105, v110, v110
	v_mul_f32_e32 v110, v106, v106
	v_lshl_add_u64 v[112:113], s[56:57], 0, v[112:113]
	v_max_f32_e32 v108, 0, v108
	v_mul_f32_e32 v104, v104, v104
	v_max_f32_e32 v105, 0, v105
	v_max_f32_e32 v106, 0, v111
	v_max_f32_e32 v107, 0, v107
	v_lshl_add_u64 v[112:113], v[112:113], 0, v[156:157]
	v_mul_f32_e32 v108, v108, v108
	v_mul_f32_e32 v105, v105, v105
	v_mul_f32_e32 v106, v106, v106
	v_mul_f32_e32 v107, v107, v107
	v_cvt_pk_bf16_f32 v104, v108, v104
	v_max_f32_e32 v96, 0, v96
	v_cvt_pk_bf16_f32 v105, v105, v106
	v_cvt_pk_bf16_f32 v106, v114, v109
	v_cvt_pk_bf16_f32 v107, v110, v107
	global_store_dwordx4 v[112:113], v[104:107], off
	s_nop 1
	v_max_f32_e32 v97, 0, v97
	v_max_f32_e32 v98, 0, v98
	v_mul_f32_e32 v104, v96, v96
	v_max_f32_e32 v96, 0, v101
	v_mul_f32_e32 v101, v97, v97
	v_max_f32_e32 v97, v102, v102
	v_mul_f32_e32 v102, v98, v98
	v_max_f32_e32 v100, 0, v100
	v_mul_f32_e32 v96, v96, v96
	v_max_f32_e32 v97, 0, v97
	v_max_f32_e32 v98, 0, v103
	v_max_f32_e32 v99, 0, v99
	v_mul_f32_e32 v100, v100, v100
	v_mul_f32_e32 v97, v97, v97
	v_mul_f32_e32 v98, v98, v98
	v_mul_f32_e32 v99, v99, v99
	v_cvt_pk_bf16_f32 v96, v100, v96
	v_cvt_pk_bf16_f32 v97, v97, v98
	v_cvt_pk_bf16_f32 v98, v104, v101
	v_cvt_pk_bf16_f32 v99, v102, v99
	global_store_dwordx4 v[112:113], v[96:99], off offset:256
	s_nop 1
	v_max_f32_e32 v88, 0, v88
	v_or_b32_e32 v96, 32, v152
	v_ashrrev_i32_e32 v97, 31, v96
	v_mul_f32_e32 v98, v88, v88
	v_max_f32_e32 v89, 0, v89
	v_max_f32_e32 v90, 0, v90
	v_lshlrev_b64 v[96:97], 13, v[96:97]
	v_max_f32_e32 v88, 0, v93
	v_mul_f32_e32 v93, v89, v89
	v_max_f32_e32 v89, v94, v94
	v_mul_f32_e32 v94, v90, v90
	v_lshl_add_u64 v[96:97], s[56:57], 0, v[96:97]
	v_max_f32_e32 v92, 0, v92
	v_mul_f32_e32 v88, v88, v88
	v_max_f32_e32 v89, 0, v89
	v_max_f32_e32 v90, 0, v95
	v_max_f32_e32 v91, 0, v91
	v_lshl_add_u64 v[96:97], v[96:97], 0, v[156:157]
	v_mul_f32_e32 v92, v92, v92
	v_mul_f32_e32 v89, v89, v89
	v_mul_f32_e32 v90, v90, v90
	v_mul_f32_e32 v91, v91, v91
	v_cvt_pk_bf16_f32 v88, v92, v88
	v_max_f32_e32 v80, 0, v80
	v_cvt_pk_bf16_f32 v89, v89, v90
	v_cvt_pk_bf16_f32 v90, v98, v93
	v_cvt_pk_bf16_f32 v91, v94, v91
	global_store_dwordx4 v[96:97], v[88:91], off
	s_nop 1
	v_max_f32_e32 v81, 0, v81
	v_max_f32_e32 v82, 0, v82
	v_mul_f32_e32 v88, v80, v80
	v_max_f32_e32 v80, 0, v85
	v_mul_f32_e32 v85, v81, v81
	v_max_f32_e32 v81, v86, v86
	v_mul_f32_e32 v86, v82, v82
	v_max_f32_e32 v84, 0, v84
	v_mul_f32_e32 v80, v80, v80
	v_max_f32_e32 v81, 0, v81
	v_max_f32_e32 v82, 0, v87
	v_max_f32_e32 v83, 0, v83
	v_mul_f32_e32 v84, v84, v84
	v_mul_f32_e32 v81, v81, v81
	v_mul_f32_e32 v82, v82, v82
	v_mul_f32_e32 v83, v83, v83
	v_cvt_pk_bf16_f32 v80, v84, v80
	v_cvt_pk_bf16_f32 v81, v81, v82
	v_cvt_pk_bf16_f32 v82, v88, v85
	v_cvt_pk_bf16_f32 v83, v86, v83
	global_store_dwordx4 v[96:97], v[80:83], off offset:256
	s_nop 1
	v_max_f32_e32 v72, 0, v72
	v_or_b32_e32 v80, 48, v152
	v_ashrrev_i32_e32 v81, 31, v80
	v_mul_f32_e32 v82, v72, v72
	v_max_f32_e32 v73, 0, v73
	v_max_f32_e32 v74, 0, v74
	v_lshlrev_b64 v[80:81], 13, v[80:81]
	v_max_f32_e32 v72, 0, v77
	v_mul_f32_e32 v77, v73, v73
	v_max_f32_e32 v73, v78, v78
	v_mul_f32_e32 v78, v74, v74
	v_lshl_add_u64 v[80:81], s[56:57], 0, v[80:81]
	v_max_f32_e32 v76, 0, v76
	v_mul_f32_e32 v72, v72, v72
	v_max_f32_e32 v73, 0, v73
	v_max_f32_e32 v74, 0, v79
	v_max_f32_e32 v75, 0, v75
	v_lshl_add_u64 v[80:81], v[80:81], 0, v[156:157]
	v_mul_f32_e32 v76, v76, v76
	v_mul_f32_e32 v73, v73, v73
	v_mul_f32_e32 v74, v74, v74
	v_mul_f32_e32 v75, v75, v75
	v_cvt_pk_bf16_f32 v72, v76, v72
	v_max_f32_e32 v64, 0, v64
	v_max_f32_e32 v65, 0, v65
	v_max_f32_e32 v66, 0, v66
	v_cvt_pk_bf16_f32 v73, v73, v74
	v_cvt_pk_bf16_f32 v74, v82, v77
	v_cvt_pk_bf16_f32 v75, v78, v75
	global_store_dwordx4 v[80:81], v[72:75], off
	s_nop 1
	v_mul_f32_e32 v72, v64, v64
	v_max_f32_e32 v64, v69, v69
	v_mul_f32_e32 v69, v65, v65
	v_max_f32_e32 v65, v70, v70
	v_mul_f32_e32 v70, v66, v66
	v_max_f32_e32 v64, 0, v64
	v_max_f32_e32 v65, 0, v65
	v_max_f32_e32 v66, 0, v71
	v_max_f32_e32 v68, 0, v68
	v_mul_f32_e32 v64, v64, v64
	v_mul_f32_e32 v65, v65, v65
	v_max_f32_e32 v67, 0, v67
	v_mul_f32_e32 v66, v66, v66
	v_mul_f32_e32 v68, v68, v68
	v_mul_f32_e32 v67, v67, v67
	v_cvt_pk_bf16_f32 v64, v68, v64
	v_cvt_pk_bf16_f32 v65, v65, v66
	v_cvt_pk_bf16_f32 v66, v72, v69
	v_max_f32_e32 v56, 0, v56
	v_cvt_pk_bf16_f32 v67, v70, v67
	global_store_dwordx4 v[80:81], v[64:67], off offset:256
	s_nop 1
	v_max_f32_e32 v57, 0, v57
	v_mul_f32_e32 v66, v56, v56
	v_max_f32_e32 v58, 0, v58
	v_max_f32_e32 v60, 0, v60
	v_max_f32_e32 v56, 0, v61
	v_mul_f32_e32 v61, v57, v57
	v_max_f32_e32 v57, v62, v62
	v_mul_f32_e32 v62, v58, v58
	v_mul_f32_e32 v60, v60, v60
	v_mul_f32_e32 v56, v56, v56
	v_max_f32_e32 v57, 0, v57
	v_max_f32_e32 v58, 0, v63
	v_mul_f32_e32 v57, v57, v57
	v_max_f32_e32 v59, 0, v59
	v_mul_f32_e32 v58, v58, v58
	v_cvt_pk_bf16_f32 v56, v60, v56
	v_add_co_u32_e32 v60, vcc, s71, v144
	v_mul_f32_e32 v59, v59, v59
	v_cvt_pk_bf16_f32 v57, v57, v58
	v_cvt_pk_bf16_f32 v58, v66, v61
	v_addc_co_u32_e32 v61, vcc, 0, v145, vcc
	v_max_f32_e32 v48, 0, v48
	v_max_f32_e32 v49, 0, v49
	v_max_f32_e32 v50, 0, v50
	v_cvt_pk_bf16_f32 v59, v62, v59
	global_store_dwordx4 v[60:61], v[56:59], off
	s_nop 1
	v_mul_f32_e32 v56, v48, v48
	v_max_f32_e32 v48, v53, v53
	v_mul_f32_e32 v53, v49, v49
	v_max_f32_e32 v49, v54, v54
	v_mul_f32_e32 v54, v50, v50
	v_max_f32_e32 v48, 0, v48
	v_max_f32_e32 v49, 0, v49
	v_max_f32_e32 v50, 0, v55
	v_max_f32_e32 v52, 0, v52
	v_mul_f32_e32 v48, v48, v48
	v_mul_f32_e32 v49, v49, v49
	v_max_f32_e32 v51, 0, v51
	v_mul_f32_e32 v50, v50, v50
	v_lshl_add_u64 v[64:65], v[144:145], 0, s[12:13]
	v_mul_f32_e32 v52, v52, v52
	v_mul_f32_e32 v51, v51, v51
	v_cvt_pk_bf16_f32 v48, v52, v48
	v_cvt_pk_bf16_f32 v49, v49, v50
	v_cvt_pk_bf16_f32 v50, v56, v53
	v_max_f32_e32 v40, 0, v40
	v_cvt_pk_bf16_f32 v51, v54, v51
	global_store_dwordx4 v[64:65], v[48:51], off offset:256
	s_nop 1
	v_max_f32_e32 v41, 0, v41
	v_mul_f32_e32 v50, v40, v40
	v_max_f32_e32 v42, 0, v42
	v_max_f32_e32 v44, 0, v44
	v_max_f32_e32 v40, 0, v45
	v_mul_f32_e32 v45, v41, v41
	v_max_f32_e32 v41, v46, v46
	v_mul_f32_e32 v46, v42, v42
	v_mul_f32_e32 v44, v44, v44
	v_mul_f32_e32 v40, v40, v40
	v_max_f32_e32 v41, 0, v41
	v_max_f32_e32 v42, 0, v47
	v_mul_f32_e32 v41, v41, v41
	v_max_f32_e32 v43, 0, v43
	v_mul_f32_e32 v42, v42, v42
	v_cvt_pk_bf16_f32 v40, v44, v40
	v_add_co_u32_e32 v44, vcc, s72, v144
	v_mul_f32_e32 v43, v43, v43
	v_cvt_pk_bf16_f32 v41, v41, v42
	v_cvt_pk_bf16_f32 v42, v50, v45
	v_addc_co_u32_e32 v45, vcc, 0, v145, vcc
	v_max_f32_e32 v32, 0, v32
	v_max_f32_e32 v33, 0, v33
	v_max_f32_e32 v34, 0, v34
	v_cvt_pk_bf16_f32 v43, v46, v43
	global_store_dwordx4 v[44:45], v[40:43], off
	s_nop 1
	v_mul_f32_e32 v40, v32, v32
	v_max_f32_e32 v32, v37, v37
	v_mul_f32_e32 v37, v33, v33
	v_max_f32_e32 v33, v38, v38
	v_mul_f32_e32 v38, v34, v34
	v_max_f32_e32 v32, 0, v32
	v_max_f32_e32 v33, 0, v33
	v_max_f32_e32 v34, 0, v39
	v_max_f32_e32 v36, 0, v36
	v_mul_f32_e32 v32, v32, v32
	v_mul_f32_e32 v33, v33, v33
	v_max_f32_e32 v35, 0, v35
	v_mul_f32_e32 v34, v34, v34
	v_lshl_add_u64 v[48:49], v[144:145], 0, s[14:15]
	v_mul_f32_e32 v36, v36, v36
	v_mul_f32_e32 v35, v35, v35
	v_cvt_pk_bf16_f32 v32, v36, v32
	v_cvt_pk_bf16_f32 v33, v33, v34
	v_cvt_pk_bf16_f32 v34, v40, v37
	v_max_f32_e32 v24, 0, v24
	v_cvt_pk_bf16_f32 v35, v38, v35
	global_store_dwordx4 v[48:49], v[32:35], off offset:256
	s_nop 1
	v_max_f32_e32 v25, 0, v25
	v_mul_f32_e32 v34, v24, v24
	v_max_f32_e32 v26, 0, v26
	v_max_f32_e32 v28, 0, v28
	v_max_f32_e32 v24, 0, v29
	v_mul_f32_e32 v29, v25, v25
	v_max_f32_e32 v25, v30, v30
	v_mul_f32_e32 v30, v26, v26
	v_mul_f32_e32 v28, v28, v28
	v_mul_f32_e32 v24, v24, v24
	v_max_f32_e32 v25, 0, v25
	v_max_f32_e32 v26, 0, v31
	v_mul_f32_e32 v25, v25, v25
	v_max_f32_e32 v27, 0, v27
	v_mul_f32_e32 v26, v26, v26
	v_cvt_pk_bf16_f32 v24, v28, v24
	v_add_co_u32_e32 v28, vcc, s73, v144
	v_mul_f32_e32 v27, v27, v27
	v_cvt_pk_bf16_f32 v25, v25, v26
	v_cvt_pk_bf16_f32 v26, v34, v29
	v_addc_co_u32_e32 v29, vcc, 0, v145, vcc
	v_max_f32_e32 v16, 0, v16
	v_max_f32_e32 v17, 0, v17
	v_max_f32_e32 v18, 0, v18
	v_cvt_pk_bf16_f32 v27, v30, v27
	global_store_dwordx4 v[28:29], v[24:27], off
	s_nop 1
	v_mul_f32_e32 v24, v16, v16
	v_max_f32_e32 v16, v21, v21
	v_mul_f32_e32 v21, v17, v17
	v_max_f32_e32 v17, v22, v22
	v_mul_f32_e32 v22, v18, v18
	v_max_f32_e32 v16, 0, v16
	v_max_f32_e32 v17, 0, v17
	v_max_f32_e32 v18, 0, v23
	v_max_f32_e32 v20, 0, v20
	v_mul_f32_e32 v16, v16, v16
	v_mul_f32_e32 v17, v17, v17
	v_max_f32_e32 v19, 0, v19
	v_mul_f32_e32 v18, v18, v18
	v_lshl_add_u64 v[32:33], v[144:145], 0, s[16:17]
	v_mul_f32_e32 v20, v20, v20
	v_mul_f32_e32 v19, v19, v19
	v_cvt_pk_bf16_f32 v16, v20, v16
	v_cvt_pk_bf16_f32 v17, v17, v18
	v_cvt_pk_bf16_f32 v18, v24, v21
	v_max_f32_e32 v8, 0, v8
	v_cvt_pk_bf16_f32 v19, v22, v19
	global_store_dwordx4 v[32:33], v[16:19], off offset:256
	s_nop 1
	v_max_f32_e32 v9, 0, v9
	v_mul_f32_e32 v18, v8, v8
	v_max_f32_e32 v10, 0, v10
	v_max_f32_e32 v12, 0, v12
	v_max_f32_e32 v8, 0, v13
	v_mul_f32_e32 v13, v9, v9
	v_max_f32_e32 v9, v14, v14
	v_mul_f32_e32 v14, v10, v10
	v_mul_f32_e32 v12, v12, v12
	v_mul_f32_e32 v8, v8, v8
	v_max_f32_e32 v9, 0, v9
	v_max_f32_e32 v10, 0, v15
	v_mul_f32_e32 v9, v9, v9
	v_max_f32_e32 v11, 0, v11
	v_mul_f32_e32 v10, v10, v10
	v_cvt_pk_bf16_f32 v8, v12, v8
	v_add_co_u32_e32 v12, vcc, s74, v144
	v_mul_f32_e32 v11, v11, v11
	v_cvt_pk_bf16_f32 v9, v9, v10
	v_cvt_pk_bf16_f32 v10, v18, v13
	v_addc_co_u32_e32 v13, vcc, 0, v145, vcc
	v_max_f32_e32 v0, 0, v0
	v_max_f32_e32 v1, 0, v1
	v_max_f32_e32 v2, 0, v2
	v_cvt_pk_bf16_f32 v11, v14, v11
	global_store_dwordx4 v[12:13], v[8:11], off
	s_nop 1
	v_mul_f32_e32 v8, v0, v0
	v_max_f32_e32 v0, v5, v5
	v_mul_f32_e32 v5, v1, v1
	v_max_f32_e32 v1, v6, v6
	v_mul_f32_e32 v6, v2, v2
	v_max_f32_e32 v0, 0, v0
	v_max_f32_e32 v1, 0, v1
	v_max_f32_e32 v2, 0, v7
	v_max_f32_e32 v3, 0, v3
	v_lshl_add_u64 v[16:17], v[144:145], 0, s[18:19]
	v_max_f32_e32 v4, 0, v4
	v_mul_f32_e32 v0, v0, v0
	v_mul_f32_e32 v1, v1, v1
	v_mul_f32_e32 v2, v2, v2
	v_mul_f32_e32 v3, v3, v3
	s_andn2_b64 vcc, exec, s[0:1]
	s_mov_b64 s[0:1], -1
	v_mul_f32_e32 v4, v4, v4
	v_cvt_pk_bf16_f32 v0, v4, v0
	v_cvt_pk_bf16_f32 v1, v1, v2
	v_cvt_pk_bf16_f32 v2, v8, v5
	v_cvt_pk_bf16_f32 v3, v6, v3
	global_store_dwordx4 v[16:17], v[0:3], off offset:256
	s_nop 1
	s_cbranch_vccnz .LBB0_1563
	s_andn2_b64 vcc, exec, s[6:7]
	s_cbranch_vccnz .LBB0_1562
	s_barrier
	s_branch .LBB0_1562
